# P1 swiglu epilogue: 8 row-stat loads hoisted above the align barrier, one wait
# speedup vs baseline: 1.0068x; 1.0068x over previous
; #define PG8_STAGE(bufoff, gbase, voff) do { _Pragma("unroll") for (int _i = 0; _i < 2; ++_i) \
;         __builtin_amdgcn_global_load_lds((const unsigned*)((const char*)(gbase) + (voff)[_i]), (PG8_LAS unsigned*)(lds + (bufoff) + ldsw + _i * 8192), 16, 0, 0); } while (0)
; #define PG8_LDA(dst, b, h) do { _Pragma("unroll") for (int m = 0; m < 4; ++m) _Pragma("unroll") for (int k = 0; k < 2; ++k) dst[m][k] = *(const PG8_LAS bf16x8*)(lds + PG8_SA(b, h) + aoff + m * 2048 + k * 1024); } while (0)
; #define PG8_LDB(dst, b, h) do { _Pragma("unroll") for (int n = 0; n < 2; ++n) _Pragma("unroll") for (int k = 0; k < 2; ++k) dst[n][k] = *(const PG8_LAS bf16x8*)(lds + PG8_SB(b, h) + boff + n * 2048 + k * 1024); } while (0)
; #define PG8_MMA(ai, bj, At, Bt) do { __builtin_amdgcn_s_setprio(1); _Pragma("unroll") for (int m = 0; m < 4; ++m) _Pragma("unroll") for (int n = 0; n < 2; ++n) _Pragma("unroll") for (int k = 0; k < 2; ++k) \
;         acc[ai][bj][m][n] = __builtin_amdgcn_mfma_f32_16x16x32_bf16(Bt[n][k], At[m][k], acc[ai][bj][m][n], 0, 0, 0); __builtin_amdgcn_s_setprio(0); } while (0)
; #define PG8_WAIT_V(n) asm volatile("s_waitcnt vmcnt(" #n ")" ::: "memory")
; #define PG8_WAIT_L(n) asm volatile("s_waitcnt lgkmcnt(" #n ")" ::: "memory")
; #define PG8_BAR __builtin_amdgcn_s_barrier()
; #define PG8_SCHED __builtin_amdgcn_sched_barrier(0)
; template <class Epi, class Sched, bool ALIGN_EPI = false, bool SP2 = false>
; __device__ __forceinline__ void gemm_phase(PG8_LAS unsigned char* lds, const Gemm g, const Sched& S, const Epi& E) {
;     ...
;             PG8_LDB(B0, 0, 0); PG8_LDB(B1, 0, 1); PG8_SCHED; PG8_LDA(At, 0, 0); PG8_STAGE(PG8_SA(1, 1), a1 + hstep, voffA);
;             PG8_WAIT_V(8); PG8_WAIT_L(0); PG8_BAR; PG8_MMA(0, 0, At, B0); PG8_MMA(0, 1, At, B1); PG8_BAR; PG8_SCHED;
;             PG8_LDA(At, 0, 1); PG8_STAGE(PG8_SB(0, 0), b2, voffB); PG8_STAGE(PG8_SB(0, 1), b2 + hstep, voffB); PG8_STAGE(PG8_SA(0, 0), a2, voffA);
;             PG8_WAIT_V(8); PG8_WAIT_L(0); PG8_BAR; PG8_MMA(1, 0, At, B0); PG8_MMA(1, 1, At, B1); PG8_BAR; PG8_SCHED;
.LBB0_143:
	ds_read_b128 v[144:147], v163
	ds_read_b128 v[168:171], v163 offset:1024
	ds_read_b128 v[172:175], v163 offset:2048
	ds_read_b128 v[176:179], v163 offset:3072
	ds_read_b128 v[180:183], v164
	ds_read_b128 v[184:187], v164 offset:1024
	ds_read_b128 v[188:191], v164 offset:2048
	ds_read_b128 v[192:195], v164 offset:3072
	s_add_u32 s40, s38, 0xfffc0080
	s_addc_u32 s41, s39, -1
	s_cmp_eq_u32 s85, 12
	s_cselect_b32 s43, s7, s41
	s_cselect_b32 s42, s29, s40
	s_cselect_b32 s41, s27, s84
	s_cselect_b32 s40, s82, s83
	v_lshl_add_u64 v[148:149], s[38:39], 0, v[136:137]
	s_add_i32 m0, s37, 0xc000
	ds_read_b128 v[196:199], v165
	ds_read_b128 v[200:203], v165 offset:1024
	ds_read_b128 v[204:207], v165 offset:2048
	ds_read_b128 v[210:213], v165 offset:3072
	ds_read_b128 v[214:217], v165 offset:4096
	ds_read_b128 v[218:221], v165 offset:5120
	ds_read_b128 v[222:225], v165 offset:6144
	ds_read_b128 v[226:229], v165 offset:7168
	global_load_lds_dwordx4 v[148:149], off
	v_lshl_add_u64 v[148:149], s[38:39], 0, v[138:139]
	s_add_i32 m0, s37, 0xe000
	s_nop 0
	global_load_lds_dwordx4 v[148:149], off
	s_waitcnt vmcnt(8)
	s_waitcnt lgkmcnt(0)
	s_barrier
	s_setprio 1
	s_waitcnt lgkmcnt(0)
	v_mfma_f32_16x16x32_bf16 v[124:127], v[144:147], v[196:199], v[124:127]
	v_mfma_f32_16x16x32_bf16 v[116:119], v[172:175], v[196:199], v[116:119]
	v_mfma_f32_16x16x32_bf16 v[108:111], v[144:147], v[204:207], v[108:111]
	v_mfma_f32_16x16x32_bf16 v[100:103], v[172:175], v[204:207], v[100:103]
	v_mfma_f32_16x16x32_bf16 v[92:95], v[144:147], v[214:217], v[92:95]
	v_mfma_f32_16x16x32_bf16 v[84:87], v[172:175], v[214:217], v[84:87]
	v_mfma_f32_16x16x32_bf16 v[76:79], v[144:147], v[222:225], v[76:79]
	v_mfma_f32_16x16x32_bf16 v[68:71], v[172:175], v[222:225], v[68:71]
	v_mfma_f32_16x16x32_bf16 v[124:127], v[168:171], v[200:203], v[124:127]
	v_mfma_f32_16x16x32_bf16 v[116:119], v[176:179], v[200:203], v[116:119]
	v_mfma_f32_16x16x32_bf16 v[108:111], v[168:171], v[210:213], v[108:111]
	v_mfma_f32_16x16x32_bf16 v[100:103], v[176:179], v[210:213], v[100:103]
	v_mfma_f32_16x16x32_bf16 v[92:95], v[168:171], v[218:221], v[92:95]
	v_mfma_f32_16x16x32_bf16 v[84:87], v[176:179], v[218:221], v[84:87]
	v_mfma_f32_16x16x32_bf16 v[76:79], v[168:171], v[226:229], v[76:79]
	v_mfma_f32_16x16x32_bf16 v[68:71], v[176:179], v[226:229], v[68:71]
	s_setprio 0
	s_setprio 1
	v_mfma_f32_16x16x32_bf16 v[120:123], v[180:183], v[196:199], v[120:123]
	v_mfma_f32_16x16x32_bf16 v[112:115], v[188:191], v[196:199], v[112:115]
	v_mfma_f32_16x16x32_bf16 v[104:107], v[180:183], v[204:207], v[104:107]
	v_mfma_f32_16x16x32_bf16 v[96:99], v[188:191], v[204:207], v[96:99]
	v_mfma_f32_16x16x32_bf16 v[88:91], v[180:183], v[214:217], v[88:91]
	v_mfma_f32_16x16x32_bf16 v[80:83], v[188:191], v[214:217], v[80:83]
	v_mfma_f32_16x16x32_bf16 v[72:75], v[180:183], v[222:225], v[72:75]
	v_mfma_f32_16x16x32_bf16 v[64:67], v[188:191], v[222:225], v[64:67]
	v_mfma_f32_16x16x32_bf16 v[120:123], v[184:187], v[200:203], v[120:123]
	v_mfma_f32_16x16x32_bf16 v[112:115], v[192:195], v[200:203], v[112:115]
	v_mfma_f32_16x16x32_bf16 v[104:107], v[184:187], v[210:213], v[104:107]
	v_mfma_f32_16x16x32_bf16 v[96:99], v[192:195], v[210:213], v[96:99]
	v_mfma_f32_16x16x32_bf16 v[88:91], v[184:187], v[218:221], v[88:91]
	v_mfma_f32_16x16x32_bf16 v[80:83], v[192:195], v[218:221], v[80:83]
	v_mfma_f32_16x16x32_bf16 v[72:75], v[184:187], v[226:229], v[72:75]
	v_mfma_f32_16x16x32_bf16 v[64:67], v[192:195], v[226:229], v[64:67]
	s_setprio 0
	s_barrier
	s_add_i32 s52, s77, s64
	v_lshl_add_u64 v[148:149], s[40:41], 0, v[130:131]
	s_mov_b32 m0, s52
	ds_read_b128 v[196:199], v165 offset:16384
	ds_read_b128 v[200:203], v165 offset:17408
	ds_read_b128 v[204:207], v165 offset:18432
	ds_read_b128 v[210:213], v165 offset:19456
	ds_read_b128 v[214:217], v165 offset:20480
	ds_read_b128 v[218:221], v165 offset:21504
	ds_read_b128 v[222:225], v165 offset:22528
	ds_read_b128 v[226:229], v165 offset:23552
	global_load_lds_dwordx4 v[148:149], off
	s_add_i32 m0, s52, 0x2000
	s_add_u32 s86, s40, 0x40000
	v_lshl_add_u64 v[230:231], s[40:41], 0, v[134:135]
	s_addc_u32 s87, s41, 0
	s_add_i32 s52, s79, s64
	global_load_lds_dwordx4 v[230:231], off
	v_lshl_add_u64 v[232:233], s[86:87], 0, v[130:131]
	s_mov_b32 m0, s52
	v_lshl_add_u64 v[234:235], s[42:43], 0, v[132:133]
	global_load_lds_dwordx4 v[232:233], off
	v_lshl_add_u64 v[232:233], s[86:87], 0, v[134:135]
	s_add_i32 m0, s52, 0x2000
	s_nop 0
	global_load_lds_dwordx4 v[232:233], off
	v_lshl_add_u64 v[232:233], s[42:43], 0, v[128:129]
	s_mov_b32 m0, s37
	s_nop 0
	global_load_lds_dwordx4 v[232:233], off
	s_mov_b32 m0, s65
	s_nop 0
	global_load_lds_dwordx4 v[234:235], off
	s_waitcnt vmcnt(8)
	s_waitcnt lgkmcnt(0)
	s_barrier
; #define PG8_STAGE(bufoff, gbase, voff) do { _Pragma("unroll") for (int _i = 0; _i < 2; ++_i) \
;         __builtin_amdgcn_global_load_lds((const unsigned*)((const char*)(gbase) + (voff)[_i]), (PG8_LAS unsigned*)(lds + (bufoff) + ldsw + _i * 8192), 16, 0, 0); } while (0)
; #define PG8_LDA(dst, b, h) do { _Pragma("unroll") for (int m = 0; m < 4; ++m) _Pragma("unroll") for (int k = 0; k < 2; ++k) dst[m][k] = *(const PG8_LAS bf16x8*)(lds + PG8_SA(b, h) + aoff + m * 2048 + k * 1024); } while (0)
; #define PG8_LDB(dst, b, h) do { _Pragma("unroll") for (int n = 0; n < 2; ++n) _Pragma("unroll") for (int k = 0; k < 2; ++k) dst[n][k] = *(const PG8_LAS bf16x8*)(lds + PG8_SB(b, h) + boff + n * 2048 + k * 1024); } while (0)
; #define PG8_MMA(ai, bj, At, Bt) do { __builtin_amdgcn_s_setprio(1); _Pragma("unroll") for (int m = 0; m < 4; ++m) _Pragma("unroll") for (int n = 0; n < 2; ++n) _Pragma("unroll") for (int k = 0; k < 2; ++k) \
;         acc[ai][bj][m][n] = __builtin_amdgcn_mfma_f32_16x16x32_bf16(Bt[n][k], At[m][k], acc[ai][bj][m][n], 0, 0, 0); __builtin_amdgcn_s_setprio(0); } while (0)
; #define PG8_WAIT_V(n) asm volatile("s_waitcnt vmcnt(" #n ")" ::: "memory")
; #define PG8_WAIT_L(n) asm volatile("s_waitcnt lgkmcnt(" #n ")" ::: "memory")
; #define PG8_BAR __builtin_amdgcn_s_barrier()
; #define PG8_SCHED __builtin_amdgcn_sched_barrier(0)
; template <class Epi, class Sched, bool ALIGN_EPI = false, bool SP2 = false>
; __device__ __forceinline__ void gemm_phase(PG8_LAS unsigned char* lds, const Gemm g, const Sched& S, const Epi& E) {
;     ...
;             PG8_WAIT_V(8); PG8_WAIT_L(0); PG8_BAR; PG8_MMA(1, 0, At, B0); PG8_MMA(1, 1, At, B1); PG8_BAR; PG8_SCHED;
;             PG8_LDB(B0, 1, 0); PG8_LDB(B1, 1, 1); PG8_SCHED; PG8_LDA(At, 1, 0); PG8_STAGE(PG8_SA(0, 1), a2 + hstep, voffA);
;             PG8_WAIT_V(8); PG8_WAIT_L(0); PG8_BAR; PG8_MMA(0, 0, At, B0); PG8_MMA(0, 1, At, B1); PG8_BAR; PG8_SCHED;
	s_setprio 1
	s_waitcnt lgkmcnt(0)
	v_mfma_f32_16x16x32_bf16 v[60:63], v[144:147], v[196:199], v[60:63]
	v_mfma_f32_16x16x32_bf16 v[52:55], v[172:175], v[196:199], v[52:55]
	v_mfma_f32_16x16x32_bf16 v[44:47], v[144:147], v[204:207], v[44:47]
	v_mfma_f32_16x16x32_bf16 v[36:39], v[172:175], v[204:207], v[36:39]
	v_mfma_f32_16x16x32_bf16 v[28:31], v[144:147], v[214:217], v[28:31]
	v_mfma_f32_16x16x32_bf16 v[20:23], v[172:175], v[214:217], v[20:23]
	v_mfma_f32_16x16x32_bf16 v[12:15], v[144:147], v[222:225], v[12:15]
	v_mfma_f32_16x16x32_bf16 v[4:7], v[172:175], v[222:225], v[4:7]
	v_mfma_f32_16x16x32_bf16 v[60:63], v[168:171], v[200:203], v[60:63]
	v_mfma_f32_16x16x32_bf16 v[52:55], v[176:179], v[200:203], v[52:55]
	v_mfma_f32_16x16x32_bf16 v[44:47], v[168:171], v[210:213], v[44:47]
	v_mfma_f32_16x16x32_bf16 v[36:39], v[176:179], v[210:213], v[36:39]
	v_mfma_f32_16x16x32_bf16 v[28:31], v[168:171], v[218:221], v[28:31]
	v_mfma_f32_16x16x32_bf16 v[20:23], v[176:179], v[218:221], v[20:23]
	v_mfma_f32_16x16x32_bf16 v[12:15], v[168:171], v[226:229], v[12:15]
	v_mfma_f32_16x16x32_bf16 v[4:7], v[176:179], v[226:229], v[4:7]
	s_setprio 0
	s_setprio 1
	v_mfma_f32_16x16x32_bf16 v[56:59], v[180:183], v[196:199], v[56:59]
	v_mfma_f32_16x16x32_bf16 v[48:51], v[188:191], v[196:199], v[48:51]
	v_mfma_f32_16x16x32_bf16 v[40:43], v[180:183], v[204:207], v[40:43]
	v_mfma_f32_16x16x32_bf16 v[32:35], v[188:191], v[204:207], v[32:35]
	v_mfma_f32_16x16x32_bf16 v[24:27], v[180:183], v[214:217], v[24:27]
	v_mfma_f32_16x16x32_bf16 v[16:19], v[188:191], v[214:217], v[16:19]
	v_mfma_f32_16x16x32_bf16 v[8:11], v[180:183], v[222:225], v[8:11]
	v_mfma_f32_16x16x32_bf16 v[0:3], v[188:191], v[222:225], v[0:3]
	v_mfma_f32_16x16x32_bf16 v[56:59], v[184:187], v[200:203], v[56:59]
	v_mfma_f32_16x16x32_bf16 v[48:51], v[192:195], v[200:203], v[48:51]
	v_mfma_f32_16x16x32_bf16 v[40:43], v[184:187], v[210:213], v[40:43]
	v_mfma_f32_16x16x32_bf16 v[32:35], v[192:195], v[210:213], v[32:35]
	v_mfma_f32_16x16x32_bf16 v[24:27], v[184:187], v[218:221], v[24:27]
	v_mfma_f32_16x16x32_bf16 v[16:19], v[192:195], v[218:221], v[16:19]
	v_mfma_f32_16x16x32_bf16 v[8:11], v[184:187], v[226:229], v[8:11]
	v_mfma_f32_16x16x32_bf16 v[0:3], v[192:195], v[226:229], v[0:3]
	s_setprio 0
	s_barrier
	s_add_i32 s52, 0, 0x18000
	v_add_u32_e32 v150, s52, v161
	s_add_i32 s53, 0, 0x1c000
	ds_read_b128 v[144:147], v150
	ds_read_b128 v[168:171], v150 offset:1024
	ds_read_b128 v[172:175], v150 offset:2048
	ds_read_b128 v[176:179], v150 offset:3072
	v_add_u32_e32 v150, s53, v161
	ds_read_b128 v[180:183], v150
	ds_read_b128 v[184:187], v150 offset:1024
	ds_read_b128 v[188:191], v150 offset:2048
	ds_read_b128 v[192:195], v150 offset:3072
	s_add_u32 s42, s42, 0x40000
	s_addc_u32 s43, s43, 0
	s_mov_b32 m0, s66
	v_lshl_add_u64 v[236:237], s[42:43], 0, v[128:129]
	ds_read_b128 v[196:199], v165 offset:32768
	ds_read_b128 v[200:203], v165 offset:33792
	ds_read_b128 v[204:207], v165 offset:34816
	ds_read_b128 v[210:213], v165 offset:35840
	ds_read_b128 v[214:217], v165 offset:36864
	ds_read_b128 v[218:221], v165 offset:37888
	ds_read_b128 v[222:225], v165 offset:38912
	ds_read_b128 v[226:229], v165 offset:39936
	global_load_lds_dwordx4 v[236:237], off
	v_lshl_add_u64 v[236:237], s[42:43], 0, v[132:133]
	s_mov_b32 m0, s67
	s_nop 0
	global_load_lds_dwordx4 v[236:237], off
	s_waitcnt vmcnt(8)
	s_waitcnt lgkmcnt(0)
	s_barrier
	s_setprio 1
	s_waitcnt lgkmcnt(0)
	v_mfma_f32_16x16x32_bf16 v[124:127], v[144:147], v[196:199], v[124:127]
	v_mfma_f32_16x16x32_bf16 v[116:119], v[172:175], v[196:199], v[116:119]
	v_mfma_f32_16x16x32_bf16 v[108:111], v[144:147], v[204:207], v[108:111]
	v_mfma_f32_16x16x32_bf16 v[100:103], v[172:175], v[204:207], v[100:103]
	v_mfma_f32_16x16x32_bf16 v[92:95], v[144:147], v[214:217], v[92:95]
	v_mfma_f32_16x16x32_bf16 v[84:87], v[172:175], v[214:217], v[84:87]
	v_mfma_f32_16x16x32_bf16 v[76:79], v[144:147], v[222:225], v[76:79]
	v_mfma_f32_16x16x32_bf16 v[68:71], v[172:175], v[222:225], v[68:71]
	v_mfma_f32_16x16x32_bf16 v[124:127], v[168:171], v[200:203], v[124:127]
	v_mfma_f32_16x16x32_bf16 v[116:119], v[176:179], v[200:203], v[116:119]
	v_mfma_f32_16x16x32_bf16 v[108:111], v[168:171], v[210:213], v[108:111]
	v_mfma_f32_16x16x32_bf16 v[100:103], v[176:179], v[210:213], v[100:103]
	v_mfma_f32_16x16x32_bf16 v[92:95], v[168:171], v[218:221], v[92:95]
	v_mfma_f32_16x16x32_bf16 v[84:87], v[176:179], v[218:221], v[84:87]
	v_mfma_f32_16x16x32_bf16 v[76:79], v[168:171], v[226:229], v[76:79]
	v_mfma_f32_16x16x32_bf16 v[68:71], v[176:179], v[226:229], v[68:71]
	s_setprio 0
	s_setprio 1
	v_mfma_f32_16x16x32_bf16 v[120:123], v[180:183], v[196:199], v[120:123]
	v_mfma_f32_16x16x32_bf16 v[112:115], v[188:191], v[196:199], v[112:115]
	v_mfma_f32_16x16x32_bf16 v[104:107], v[180:183], v[204:207], v[104:107]
	v_mfma_f32_16x16x32_bf16 v[96:99], v[188:191], v[204:207], v[96:99]
	v_mfma_f32_16x16x32_bf16 v[88:91], v[180:183], v[214:217], v[88:91]
	v_mfma_f32_16x16x32_bf16 v[80:83], v[188:191], v[214:217], v[80:83]
	v_mfma_f32_16x16x32_bf16 v[72:75], v[180:183], v[222:225], v[72:75]
	v_mfma_f32_16x16x32_bf16 v[64:67], v[188:191], v[222:225], v[64:67]
	v_mfma_f32_16x16x32_bf16 v[120:123], v[184:187], v[200:203], v[120:123]
	v_mfma_f32_16x16x32_bf16 v[112:115], v[192:195], v[200:203], v[112:115]
	v_mfma_f32_16x16x32_bf16 v[104:107], v[184:187], v[210:213], v[104:107]
	v_mfma_f32_16x16x32_bf16 v[96:99], v[192:195], v[210:213], v[96:99]
	v_mfma_f32_16x16x32_bf16 v[88:91], v[184:187], v[218:221], v[88:91]
	v_mfma_f32_16x16x32_bf16 v[80:83], v[192:195], v[218:221], v[80:83]
	v_mfma_f32_16x16x32_bf16 v[72:75], v[184:187], v[226:229], v[72:75]
	v_mfma_f32_16x16x32_bf16 v[64:67], v[192:195], v[226:229], v[64:67]
	s_setprio 0
	s_barrier
; #define PG8_STAGE(bufoff, gbase, voff) do { _Pragma("unroll") for (int _i = 0; _i < 2; ++_i) \
;         __builtin_amdgcn_global_load_lds((const unsigned*)((const char*)(gbase) + (voff)[_i]), (PG8_LAS unsigned*)(lds + (bufoff) + ldsw + _i * 8192), 16, 0, 0); } while (0)
; #define PG8_LDA(dst, b, h) do { _Pragma("unroll") for (int m = 0; m < 4; ++m) _Pragma("unroll") for (int k = 0; k < 2; ++k) dst[m][k] = *(const PG8_LAS bf16x8*)(lds + PG8_SA(b, h) + aoff + m * 2048 + k * 1024); } while (0)
; #define PG8_MMA(ai, bj, At, Bt) do { __builtin_amdgcn_s_setprio(1); _Pragma("unroll") for (int m = 0; m < 4; ++m) _Pragma("unroll") for (int n = 0; n < 2; ++n) _Pragma("unroll") for (int k = 0; k < 2; ++k) \
;         acc[ai][bj][m][n] = __builtin_amdgcn_mfma_f32_16x16x32_bf16(Bt[n][k], At[m][k], acc[ai][bj][m][n], 0, 0, 0); __builtin_amdgcn_s_setprio(0); } while (0)
; #define PG8_WAIT_V(n) asm volatile("s_waitcnt vmcnt(" #n ")" ::: "memory")
; #define PG8_WAIT_L(n) asm volatile("s_waitcnt lgkmcnt(" #n ")" ::: "memory")
; #define PG8_BAR __builtin_amdgcn_s_barrier()
; #define PG8_SCHED __builtin_amdgcn_sched_barrier(0)
; template <class Epi, class Sched, bool ALIGN_EPI = false, bool SP2 = false>
; __device__ __forceinline__ void gemm_phase(PG8_LAS unsigned char* lds, const Gemm g, const Sched& S, const Epi& E) {
;     ...
;             PG8_LDA(At, 1, 1); PG8_STAGE(PG8_SB(1, 0), b3, voffB); PG8_STAGE(PG8_SB(1, 1), b3 + hstep, voffB); PG8_STAGE(PG8_SA(1, 0), a3, voffA);
;             PG8_WAIT_V(8); PG8_WAIT_L(0); PG8_BAR; PG8_MMA(1, 0, At, B0); PG8_MMA(1, 1, At, B1); PG8_BAR; PG8_SCHED;
; __device__ __forceinline__ float row_rs(const float* ssq, int row) { return ssq ? rsqrtf(ssq[row] * (1.f / 1024.f) + RMS_EPS) : 1.f; }
;     __device__ __forceinline__ void operator()(const f32x4 (&acc)[2][2][4][2], const Unit& u, int wr, int wc, int fr, int fq) const {
;         const int row0 = u.pm * BM + wr * 64 + fr, col0 = u.pn * HALF + wc * 32 + 8 * fq;
; #pragma unroll
;         for (int ai = 0; ai < 2; ++ai)
; #pragma unroll
;             for (int m = 0; m < 4; ++m) { const int row = row0 + ai * HALF + m * 16; const float rs = row_rs(ssq, row);
	s_add_i32 s42, s52, s64
	v_lshl_add_u64 v[148:149], v[148:149], 0, s[16:17]
	s_mov_b32 m0, s42
	ds_read_b128 v[196:199], v165 offset:49152
	ds_read_b128 v[200:203], v165 offset:50176
	ds_read_b128 v[204:207], v165 offset:51200
	ds_read_b128 v[210:213], v165 offset:52224
	ds_read_b128 v[214:217], v165 offset:53248
	ds_read_b128 v[218:221], v165 offset:54272
	ds_read_b128 v[222:225], v165 offset:55296
	ds_read_b128 v[226:229], v165 offset:56320
	global_load_lds_dwordx4 v[148:149], off
	s_add_i32 m0, s42, 0x2000
	s_add_u32 s40, s40, 0x40080
	v_lshl_add_u64 v[148:149], v[230:231], 0, s[16:17]
	s_addc_u32 s41, s41, 0
	s_add_i32 s42, s53, s64
	global_load_lds_dwordx4 v[148:149], off
	v_lshl_add_u64 v[148:149], s[40:41], 0, v[130:131]
	s_mov_b32 m0, s42
	s_nop 0
	global_load_lds_dwordx4 v[148:149], off
	v_lshl_add_u64 v[148:149], s[40:41], 0, v[134:135]
	s_add_i32 m0, s42, 0x2000
	s_nop 0
	global_load_lds_dwordx4 v[148:149], off
	v_lshl_add_u64 v[148:149], v[232:233], 0, s[16:17]
	s_mov_b32 m0, s74
	s_nop 0
	global_load_lds_dwordx4 v[148:149], off
	v_lshl_add_u64 v[148:149], v[234:235], 0, s[16:17]
	s_mov_b32 m0, s75
	s_nop 0
	global_load_lds_dwordx4 v[148:149], off
	s_waitcnt vmcnt(8)
	s_waitcnt lgkmcnt(0)
	s_barrier
	s_setprio 1
	s_waitcnt lgkmcnt(0)
	v_mfma_f32_16x16x32_bf16 v[60:63], v[144:147], v[196:199], v[60:63]
	v_mfma_f32_16x16x32_bf16 v[52:55], v[172:175], v[196:199], v[52:55]
	v_mfma_f32_16x16x32_bf16 v[44:47], v[144:147], v[204:207], v[44:47]
	v_mfma_f32_16x16x32_bf16 v[36:39], v[172:175], v[204:207], v[36:39]
	v_mfma_f32_16x16x32_bf16 v[28:31], v[144:147], v[214:217], v[28:31]
	v_mfma_f32_16x16x32_bf16 v[20:23], v[172:175], v[214:217], v[20:23]
	v_mfma_f32_16x16x32_bf16 v[12:15], v[144:147], v[222:225], v[12:15]
	v_mfma_f32_16x16x32_bf16 v[4:7], v[172:175], v[222:225], v[4:7]
	v_mfma_f32_16x16x32_bf16 v[60:63], v[168:171], v[200:203], v[60:63]
	v_mfma_f32_16x16x32_bf16 v[52:55], v[176:179], v[200:203], v[52:55]
	v_mfma_f32_16x16x32_bf16 v[44:47], v[168:171], v[210:213], v[44:47]
	v_mfma_f32_16x16x32_bf16 v[36:39], v[176:179], v[210:213], v[36:39]
	v_mfma_f32_16x16x32_bf16 v[28:31], v[168:171], v[218:221], v[28:31]
	v_mfma_f32_16x16x32_bf16 v[20:23], v[176:179], v[218:221], v[20:23]
	v_mfma_f32_16x16x32_bf16 v[12:15], v[168:171], v[226:229], v[12:15]
	v_mfma_f32_16x16x32_bf16 v[4:7], v[176:179], v[226:229], v[4:7]
	s_setprio 0
	s_setprio 1
	v_mfma_f32_16x16x32_bf16 v[56:59], v[180:183], v[196:199], v[56:59]
	v_mfma_f32_16x16x32_bf16 v[48:51], v[188:191], v[196:199], v[48:51]
	v_mfma_f32_16x16x32_bf16 v[40:43], v[180:183], v[204:207], v[40:43]
	v_mfma_f32_16x16x32_bf16 v[32:35], v[188:191], v[204:207], v[32:35]
	v_mfma_f32_16x16x32_bf16 v[24:27], v[180:183], v[214:217], v[24:27]
	v_mfma_f32_16x16x32_bf16 v[16:19], v[188:191], v[214:217], v[16:19]
	v_mfma_f32_16x16x32_bf16 v[8:11], v[180:183], v[222:225], v[8:11]
	v_mfma_f32_16x16x32_bf16 v[0:3], v[188:191], v[222:225], v[0:3]
	v_mfma_f32_16x16x32_bf16 v[56:59], v[184:187], v[200:203], v[56:59]
	v_mfma_f32_16x16x32_bf16 v[48:51], v[192:195], v[200:203], v[48:51]
	v_mfma_f32_16x16x32_bf16 v[40:43], v[184:187], v[210:213], v[40:43]
	v_mfma_f32_16x16x32_bf16 v[32:35], v[192:195], v[210:213], v[32:35]
	v_mfma_f32_16x16x32_bf16 v[24:27], v[184:187], v[218:221], v[24:27]
	v_mfma_f32_16x16x32_bf16 v[16:19], v[192:195], v[218:221], v[16:19]
	v_mfma_f32_16x16x32_bf16 v[8:11], v[184:187], v[226:229], v[8:11]
	v_mfma_f32_16x16x32_bf16 v[0:3], v[192:195], v[226:229], v[0:3]
	s_setprio 0
	s_barrier
	s_add_i32 s85, s85, 2
	s_add_u32 s38, s38, 0x100
	s_addc_u32 s39, s39, 0
	s_add_u32 s83, s83, 0x100
	s_addc_u32 s84, s84, 0
	s_cmp_gt_u32 s85, 13
	s_cbranch_scc0 .LBB0_143
	v_lshl_add_u32 v146, s6, 8, v160
	v_ashrrev_i32_e32 v147, 31, v146
	s_andn2_b64 vcc, exec, s[12:13]
	v_lshl_add_u64 v[148:149], v[146:147], 2, s[48:49]
	s_cbranch_vccnz .Lp1_rs_issued
	global_load_dword v172, v[148:149], off
	global_load_dword v173, v[148:149], off offset:64
	global_load_dword v174, v[148:149], off offset:128
	global_load_dword v175, v[148:149], off offset:192
	global_load_dword v176, v[148:149], off offset:512
	global_load_dword v177, v[148:149], off offset:576
	global_load_dword v178, v[148:149], off offset:640
	global_load_dword v179, v[148:149], off offset:704
.Lp1_rs_issued:
	s_and_b64 vcc, exec, s[18:19]
	s_cbranch_vccz .LBB0_146
	s_barrier
.LBB0_146:
	v_cndmask_b32_e64 v144, 0, 1, s[12:13]
	v_mov_b32_e32 v150, 1.0
	v_cmp_ne_u32_e64 s[6:7], 1, v144
	s_andn2_b64 vcc, exec, s[12:13]
	v_mov_b32_e32 v152, 1.0
	s_cbranch_vccnz .LBB0_148
	s_waitcnt vmcnt(0)
	v_fmamk_f32 v144, v172, 0x3a800000, v166
	v_mul_f32_e32 v145, 0x4b800000, v144
	v_cmp_gt_f32_e32 vcc, s80, v144
	s_nop 1
	v_cndmask_b32_e32 v144, v144, v145, vcc
	v_rsq_f32_e32 v144, v144
	s_nop 0
	v_mul_f32_e32 v145, 0x45800000, v144
	v_cndmask_b32_e32 v152, v144, v145, vcc
; __device__ __forceinline__ unsigned cvt_pk_bf16(float lo, float hi) { cvf32x2_t v = {lo, hi}; cvbf16x2_t b = __builtin_convertvector(v, cvbf16x2_t); return __builtin_bit_cast(unsigned, b); }
; __device__ __forceinline__ float fsilu(float x) { return x * fsigm(x); }
; __device__ __forceinline__ float row_rs(const float* ssq, int row) { return ssq ? rsqrtf(ssq[row] * (1.f / 1024.f) + RMS_EPS) : 1.f; }
;     __device__ __forceinline__ void operator()(const f32x4 (&acc)[2][2][4][2], const Unit& u, int wr, int wc, int fr, int fq) const {
;     ...
;             for (int m = 0; m < 4; ++m) { const int row = row0 + ai * HALF + m * 16; const float rs = row_rs(ssq, row);
;                 u32x4 w; unsigned pk[4];
; #pragma unroll
;                 for (int n = 0; n < 2; ++n) { const f32x4 g = acc[ai][0][m][n] * rs, up = acc[ai][1][m][n] * rs;
;                     pk[2 * n] = cvt_pk_bf16(fsilu(g[0]) * up[0], fsilu(g[1]) * up[1]); pk[2 * n + 1] = cvt_pk_bf16(fsilu(g[2]) * up[2], fsilu(g[3]) * up[3]); }
;                 w.x = pk[0]; w.y = pk[1]; w.z = pk[2]; w.w = pk[3];
;                 st_wt16(H + (size_t)row * ldh + col0, w); }
.LBB0_148:
	v_pk_mul_f32 v[124:125], v[124:125], v[152:153] op_sel_hi:[1,0]
	v_pk_mul_f32 v[126:127], v[126:127], v[152:153] op_sel_hi:[1,0]
	v_mul_f32_e32 v147, 0xbfb8aa3b, v124
	v_exp_f32_e32 v147, v147
	v_mul_f32_e32 v167, 0xbfb8aa3b, v125
	v_exp_f32_e32 v167, v167
	v_mul_f32_e32 v169, 0xbfb8aa3b, v127
	v_add_f32_e32 v147, 1.0, v147
	v_rcp_f32_e32 v168, v147
	v_add_f32_e32 v147, 1.0, v167
	v_mul_f32_e32 v167, 0xbfb8aa3b, v126
	v_exp_f32_e32 v167, v167
	v_exp_f32_e32 v171, v169
	v_rcp_f32_e32 v169, v147
	v_pk_mul_f32 v[120:121], v[120:121], v[152:153] op_sel_hi:[1,0]
	v_add_f32_e32 v147, 1.0, v167
	v_rcp_f32_e32 v170, v147
	v_add_f32_e32 v147, 1.0, v171
	v_rcp_f32_e32 v171, v147
	v_pk_mul_f32 v[124:125], v[124:125], v[168:169]
	v_pk_mul_f32 v[122:123], v[122:123], v[152:153] op_sel_hi:[1,0]
	v_pk_mul_f32 v[120:121], v[120:121], v[124:125]
	v_pk_mul_f32 v[124:125], v[126:127], v[170:171]
	v_pk_mul_f32 v[116:117], v[116:117], v[152:153] op_sel_hi:[1,0]
	v_pk_mul_f32 v[122:123], v[122:123], v[124:125]
	v_cvt_pk_bf16_f32 v120, v120, v121
	v_cvt_pk_bf16_f32 v121, v122, v123
	v_mul_f32_e32 v122, 0xbfb8aa3b, v116
	v_mul_f32_e32 v123, 0xbfb8aa3b, v117
	v_pk_mul_f32 v[118:119], v[118:119], v[152:153] op_sel_hi:[1,0]
	v_exp_f32_e32 v122, v122
	v_exp_f32_e32 v123, v123
	v_mul_f32_e32 v124, 0xbfb8aa3b, v118
	v_mul_f32_e32 v125, 0xbfb8aa3b, v119
	v_exp_f32_e32 v124, v124
	v_exp_f32_e32 v125, v125
	v_add_f32_e32 v122, 1.0, v122
	v_add_f32_e32 v123, 1.0, v123
	v_rcp_f32_e32 v122, v122
	v_rcp_f32_e32 v123, v123
	v_add_f32_e32 v124, 1.0, v124
	v_add_f32_e32 v125, 1.0, v125
	v_rcp_f32_e32 v124, v124
	v_rcp_f32_e32 v125, v125
	v_pk_mul_f32 v[112:113], v[112:113], v[152:153] op_sel_hi:[1,0]
	v_pk_mul_f32 v[116:117], v[116:117], v[122:123]
	v_pk_mul_f32 v[114:115], v[114:115], v[152:153] op_sel_hi:[1,0]
	v_pk_mul_f32 v[112:113], v[112:113], v[116:117]
	v_lshl_or_b32 v144, s36, 7, v162
	v_cvt_pk_bf16_f32 v122, v112, v113
	v_pk_mul_f32 v[112:113], v[118:119], v[124:125]
	v_ashrrev_i32_e32 v145, 31, v144
	v_pk_mul_f32 v[112:113], v[114:115], v[112:113]
	s_and_b64 vcc, exec, s[6:7]
	v_cvt_pk_bf16_f32 v123, v112, v113
	v_mov_b64_e32 v[112:113], s[56:57]
	v_mad_i64_i32 v[112:113], s[38:39], v146, s81, v[112:113]
	v_lshl_add_u64 v[112:113], v[144:145], 1, v[112:113]
	global_store_dwordx4 v[112:113], v[120:123], off
	s_cbranch_vccnz .LBB0_150
	v_fmamk_f32 v112, v173, 0x3a800000, v166
	v_mul_f32_e32 v113, 0x4b800000, v112
	v_cmp_gt_f32_e32 vcc, s80, v112
	s_nop 1
	v_cndmask_b32_e32 v112, v112, v113, vcc
	v_rsq_f32_e32 v112, v112
	s_nop 0
	v_mul_f32_e32 v113, 0x45800000, v112
	v_cndmask_b32_e32 v150, v112, v113, vcc
.LBB0_150:
	v_pk_mul_f32 v[108:109], v[108:109], v[150:151] op_sel_hi:[1,0]
	v_pk_mul_f32 v[112:113], v[106:107], v[150:151] op_sel_hi:[1,0]
	v_pk_mul_f32 v[106:107], v[104:105], v[150:151] op_sel_hi:[1,0]
	v_mul_f32_e32 v104, 0xbfb8aa3b, v108
	v_exp_f32_e32 v105, v104
	v_mul_f32_e32 v104, 0xbfb8aa3b, v109
	v_exp_f32_e32 v115, v104
	v_pk_mul_f32 v[110:111], v[110:111], v[150:151] op_sel_hi:[1,0]
	v_add_f32_e32 v105, 1.0, v105
	v_rcp_f32_e32 v114, v105
	v_add_f32_e32 v105, 1.0, v115
	v_mul_f32_e32 v115, 0xbfb8aa3b, v110
	v_exp_f32_e32 v116, v115
	v_mul_f32_e32 v115, 0xbfb8aa3b, v111
	v_exp_f32_e32 v117, v115
	v_rcp_f32_e32 v115, v105
	v_add_f32_e32 v105, 1.0, v116
	v_rcp_f32_e32 v116, v105
	v_add_f32_e32 v105, 1.0, v117
	v_rcp_f32_e32 v117, v105
	v_pk_mul_f32 v[108:109], v[108:109], v[114:115]
	v_pk_mul_f32 v[100:101], v[100:101], v[150:151] op_sel_hi:[1,0]
	v_pk_mul_f32 v[106:107], v[106:107], v[108:109]
	v_pk_mul_f32 v[108:109], v[110:111], v[116:117]
	v_mul_f32_e32 v105, 0xbfb8aa3b, v100
	v_pk_mul_f32 v[108:109], v[112:113], v[108:109]
	v_cvt_pk_bf16_f32 v106, v106, v107
	v_cvt_pk_bf16_f32 v107, v108, v109
	v_exp_f32_e32 v105, v105
	v_mul_f32_e32 v108, 0xbfb8aa3b, v101
	v_exp_f32_e32 v109, v108
	v_pk_mul_f32 v[102:103], v[102:103], v[150:151] op_sel_hi:[1,0]
	v_add_f32_e32 v105, 1.0, v105
	v_rcp_f32_e32 v108, v105
	v_add_f32_e32 v105, 1.0, v109
	v_mul_f32_e32 v109, 0xbfb8aa3b, v102
	v_exp_f32_e32 v110, v109
	v_mul_f32_e32 v109, 0xbfb8aa3b, v103
	v_exp_f32_e32 v111, v109
	v_rcp_f32_e32 v109, v105
	v_add_f32_e32 v105, 1.0, v110
	v_rcp_f32_e32 v110, v105
	v_add_f32_e32 v105, 1.0, v111
	v_rcp_f32_e32 v111, v105
	v_pk_mul_f32 v[96:97], v[96:97], v[150:151] op_sel_hi:[1,0]
	v_pk_mul_f32 v[100:101], v[100:101], v[108:109]
	v_pk_mul_f32 v[98:99], v[98:99], v[150:151] op_sel_hi:[1,0]
	v_pk_mul_f32 v[96:97], v[96:97], v[100:101]
	v_or_b32_e32 v118, 16, v146
	v_cvt_pk_bf16_f32 v108, v96, v97
	v_pk_mul_f32 v[96:97], v[102:103], v[110:111]
	v_mov_b32_e32 v104, 1.0
	v_pk_mul_f32 v[96:97], v[98:99], v[96:97]
	s_and_b64 vcc, exec, s[6:7]
	v_cvt_pk_bf16_f32 v109, v96, v97
	v_mov_b64_e32 v[96:97], s[56:57]
	v_mad_i64_i32 v[96:97], s[38:39], v118, s81, v[96:97]
	v_lshl_add_u64 v[96:97], v[144:145], 1, v[96:97]
	global_store_dwordx4 v[96:97], v[106:109], off
	v_mov_b32_e32 v96, 1.0
	s_cbranch_vccnz .LBB0_152
	v_fmamk_f32 v96, v174, 0x3a800000, v166
	v_mul_f32_e32 v97, 0x4b800000, v96
	v_cmp_gt_f32_e32 vcc, s80, v96
	s_nop 1
	v_cndmask_b32_e32 v96, v96, v97, vcc
	v_rsq_f32_e32 v96, v96
	s_nop 0
	v_mul_f32_e32 v97, 0x45800000, v96
	v_cndmask_b32_e32 v96, v96, v97, vcc
; __device__ __forceinline__ unsigned cvt_pk_bf16(float lo, float hi) { cvf32x2_t v = {lo, hi}; cvbf16x2_t b = __builtin_convertvector(v, cvbf16x2_t); return __builtin_bit_cast(unsigned, b); }
; __device__ __forceinline__ float fsilu(float x) { return x * fsigm(x); }
; __device__ __forceinline__ float row_rs(const float* ssq, int row) { return ssq ? rsqrtf(ssq[row] * (1.f / 1024.f) + RMS_EPS) : 1.f; }
;     __device__ __forceinline__ void operator()(const f32x4 (&acc)[2][2][4][2], const Unit& u, int wr, int wc, int fr, int fq) const {
;     ...
;             for (int m = 0; m < 4; ++m) { const int row = row0 + ai * HALF + m * 16; const float rs = row_rs(ssq, row);
;                 u32x4 w; unsigned pk[4];
; #pragma unroll
;                 for (int n = 0; n < 2; ++n) { const f32x4 g = acc[ai][0][m][n] * rs, up = acc[ai][1][m][n] * rs;
;                     pk[2 * n] = cvt_pk_bf16(fsilu(g[0]) * up[0], fsilu(g[1]) * up[1]); pk[2 * n + 1] = cvt_pk_bf16(fsilu(g[2]) * up[2], fsilu(g[3]) * up[3]); }
;                 w.x = pk[0]; w.y = pk[1]; w.z = pk[2]; w.w = pk[3];
;                 st_wt16(H + (size_t)row * ldh + col0, w); }
.LBB0_152:
	v_or_b32_e32 v97, 32, v146
	v_pk_mul_f32 v[92:93], v[92:93], v[96:97] op_sel_hi:[1,0]
	v_pk_mul_f32 v[94:95], v[94:95], v[96:97] op_sel_hi:[1,0]
	v_mul_f32_e32 v98, 0xbfb8aa3b, v92
	v_mul_f32_e32 v99, 0xbfb8aa3b, v93
	v_exp_f32_e32 v98, v98
	v_exp_f32_e32 v99, v99
	v_mul_f32_e32 v100, 0xbfb8aa3b, v94
	v_mul_f32_e32 v101, 0xbfb8aa3b, v95
	v_exp_f32_e32 v100, v100
	v_exp_f32_e32 v101, v101
	v_add_f32_e32 v98, 1.0, v98
	v_add_f32_e32 v99, 1.0, v99
	v_rcp_f32_e32 v98, v98
	v_rcp_f32_e32 v99, v99
	v_add_f32_e32 v100, 1.0, v100
	v_add_f32_e32 v101, 1.0, v101
	v_rcp_f32_e32 v100, v100
	v_rcp_f32_e32 v101, v101
	v_pk_mul_f32 v[88:89], v[88:89], v[96:97] op_sel_hi:[1,0]
	v_pk_mul_f32 v[92:93], v[92:93], v[98:99]
	v_pk_mul_f32 v[90:91], v[90:91], v[96:97] op_sel_hi:[1,0]
	v_pk_mul_f32 v[88:89], v[88:89], v[92:93]
	v_pk_mul_f32 v[92:93], v[94:95], v[100:101]
	v_pk_mul_f32 v[84:85], v[84:85], v[96:97] op_sel_hi:[1,0]
	v_pk_mul_f32 v[90:91], v[90:91], v[92:93]
	v_cvt_pk_bf16_f32 v88, v88, v89
	v_cvt_pk_bf16_f32 v89, v90, v91
	v_mul_f32_e32 v90, 0xbfb8aa3b, v84
	v_mul_f32_e32 v91, 0xbfb8aa3b, v85
	v_pk_mul_f32 v[86:87], v[86:87], v[96:97] op_sel_hi:[1,0]
	v_exp_f32_e32 v90, v90
	v_exp_f32_e32 v91, v91
	v_mul_f32_e32 v92, 0xbfb8aa3b, v86
	v_mul_f32_e32 v93, 0xbfb8aa3b, v87
	v_exp_f32_e32 v92, v92
	v_exp_f32_e32 v93, v93
	v_add_f32_e32 v90, 1.0, v90
	v_add_f32_e32 v91, 1.0, v91
	v_rcp_f32_e32 v90, v90
	v_rcp_f32_e32 v91, v91
	v_add_f32_e32 v92, 1.0, v92
	v_add_f32_e32 v93, 1.0, v93
	v_rcp_f32_e32 v92, v92
	v_rcp_f32_e32 v93, v93
	v_pk_mul_f32 v[80:81], v[80:81], v[96:97] op_sel_hi:[1,0]
	v_pk_mul_f32 v[84:85], v[84:85], v[90:91]
	v_pk_mul_f32 v[82:83], v[82:83], v[96:97] op_sel_hi:[1,0]
	v_pk_mul_f32 v[80:81], v[80:81], v[84:85]
	s_and_b64 vcc, exec, s[6:7]
	v_cvt_pk_bf16_f32 v90, v80, v81
	v_pk_mul_f32 v[80:81], v[86:87], v[92:93]
	s_nop 0
	v_pk_mul_f32 v[80:81], v[82:83], v[80:81]
	s_nop 0
	v_cvt_pk_bf16_f32 v91, v80, v81
	v_mov_b64_e32 v[80:81], s[56:57]
	v_mad_i64_i32 v[80:81], s[38:39], v97, s81, v[80:81]
	v_lshl_add_u64 v[80:81], v[144:145], 1, v[80:81]
	global_store_dwordx4 v[80:81], v[88:91], off
	s_cbranch_vccnz .LBB0_154
	v_fmamk_f32 v80, v175, 0x3a800000, v166
	v_mul_f32_e32 v81, 0x4b800000, v80
	v_cmp_gt_f32_e32 vcc, s80, v80
	s_nop 1
	v_cndmask_b32_e32 v80, v80, v81, vcc
	v_rsq_f32_e32 v80, v80
	s_nop 0
	v_mul_f32_e32 v81, 0x45800000, v80
	v_cndmask_b32_e32 v104, v80, v81, vcc
.LBB0_154:
	v_pk_mul_f32 v[76:77], v[76:77], v[104:105] op_sel_hi:[1,0]
	v_pk_mul_f32 v[80:81], v[74:75], v[104:105] op_sel_hi:[1,0]
	v_pk_mul_f32 v[74:75], v[72:73], v[104:105] op_sel_hi:[1,0]
	v_mul_f32_e32 v72, 0xbfb8aa3b, v76
	v_exp_f32_e32 v73, v72
	v_mul_f32_e32 v72, 0xbfb8aa3b, v77
	v_exp_f32_e32 v83, v72
	v_pk_mul_f32 v[78:79], v[78:79], v[104:105] op_sel_hi:[1,0]
	v_add_f32_e32 v73, 1.0, v73
	v_rcp_f32_e32 v82, v73
	v_add_f32_e32 v73, 1.0, v83
	v_mul_f32_e32 v83, 0xbfb8aa3b, v78
	v_exp_f32_e32 v84, v83
	v_mul_f32_e32 v83, 0xbfb8aa3b, v79
	v_exp_f32_e32 v85, v83
	v_rcp_f32_e32 v83, v73
	v_add_f32_e32 v73, 1.0, v84
	v_rcp_f32_e32 v84, v73
	v_add_f32_e32 v73, 1.0, v85
	v_rcp_f32_e32 v85, v73
	v_pk_mul_f32 v[76:77], v[76:77], v[82:83]
	v_pk_mul_f32 v[68:69], v[68:69], v[104:105] op_sel_hi:[1,0]
	v_pk_mul_f32 v[74:75], v[74:75], v[76:77]
	v_pk_mul_f32 v[76:77], v[78:79], v[84:85]
	v_mul_f32_e32 v73, 0xbfb8aa3b, v68
	v_pk_mul_f32 v[76:77], v[80:81], v[76:77]
	v_cvt_pk_bf16_f32 v74, v74, v75
	v_cvt_pk_bf16_f32 v75, v76, v77
	v_exp_f32_e32 v73, v73
	v_mul_f32_e32 v76, 0xbfb8aa3b, v69
	v_exp_f32_e32 v77, v76
	v_pk_mul_f32 v[70:71], v[70:71], v[104:105] op_sel_hi:[1,0]
	v_add_f32_e32 v73, 1.0, v73
	v_rcp_f32_e32 v76, v73
	v_add_f32_e32 v73, 1.0, v77
	v_mul_f32_e32 v77, 0xbfb8aa3b, v70
	v_exp_f32_e32 v78, v77
	v_mul_f32_e32 v77, 0xbfb8aa3b, v71
	v_exp_f32_e32 v79, v77
	v_rcp_f32_e32 v77, v73
	v_add_f32_e32 v73, 1.0, v78
	v_rcp_f32_e32 v78, v73
	v_add_f32_e32 v73, 1.0, v79
	v_rcp_f32_e32 v79, v73
	v_pk_mul_f32 v[64:65], v[64:65], v[104:105] op_sel_hi:[1,0]
	v_pk_mul_f32 v[68:69], v[68:69], v[76:77]
	v_pk_mul_f32 v[66:67], v[66:67], v[104:105] op_sel_hi:[1,0]
	v_pk_mul_f32 v[64:65], v[64:65], v[68:69]
	v_or_b32_e32 v86, 48, v146
	v_cvt_pk_bf16_f32 v76, v64, v65
	v_pk_mul_f32 v[64:65], v[70:71], v[78:79]
	v_mov_b32_e32 v72, 1.0
	v_pk_mul_f32 v[64:65], v[66:67], v[64:65]
	s_and_b64 vcc, exec, s[6:7]
	v_cvt_pk_bf16_f32 v77, v64, v65
	v_mov_b64_e32 v[64:65], s[56:57]
	v_mad_i64_i32 v[64:65], s[38:39], v86, s81, v[64:65]
	v_lshl_add_u64 v[64:65], v[144:145], 1, v[64:65]
	global_store_dwordx4 v[64:65], v[74:77], off
	v_mov_b32_e32 v64, 1.0
	s_cbranch_vccnz .LBB0_156
	v_fmamk_f32 v64, v176, 0x3a800000, v166
	v_mul_f32_e32 v65, 0x4b800000, v64
	v_cmp_gt_f32_e32 vcc, s80, v64
	s_nop 1
	v_cndmask_b32_e32 v64, v64, v65, vcc
	v_rsq_f32_e32 v64, v64
	s_nop 0
	v_mul_f32_e32 v65, 0x45800000, v64
	v_cndmask_b32_e32 v64, v64, v65, vcc
; __device__ __forceinline__ unsigned cvt_pk_bf16(float lo, float hi) { cvf32x2_t v = {lo, hi}; cvbf16x2_t b = __builtin_convertvector(v, cvbf16x2_t); return __builtin_bit_cast(unsigned, b); }
; __device__ __forceinline__ float fsilu(float x) { return x * fsigm(x); }
; __device__ __forceinline__ float row_rs(const float* ssq, int row) { return ssq ? rsqrtf(ssq[row] * (1.f / 1024.f) + RMS_EPS) : 1.f; }
;     __device__ __forceinline__ void operator()(const f32x4 (&acc)[2][2][4][2], const Unit& u, int wr, int wc, int fr, int fq) const {
;     ...
;             for (int m = 0; m < 4; ++m) { const int row = row0 + ai * HALF + m * 16; const float rs = row_rs(ssq, row);
;                 u32x4 w; unsigned pk[4];
; #pragma unroll
;                 for (int n = 0; n < 2; ++n) { const f32x4 g = acc[ai][0][m][n] * rs, up = acc[ai][1][m][n] * rs;
;                     pk[2 * n] = cvt_pk_bf16(fsilu(g[0]) * up[0], fsilu(g[1]) * up[1]); pk[2 * n + 1] = cvt_pk_bf16(fsilu(g[2]) * up[2], fsilu(g[3]) * up[3]); }
;                 w.x = pk[0]; w.y = pk[1]; w.z = pk[2]; w.w = pk[3];
;                 st_wt16(H + (size_t)row * ldh + col0, w); }
.LBB0_156:
	v_add_u32_e32 v65, 0x80, v146
	v_pk_mul_f32 v[60:61], v[60:61], v[64:65] op_sel_hi:[1,0]
	v_pk_mul_f32 v[62:63], v[62:63], v[64:65] op_sel_hi:[1,0]
	v_mul_f32_e32 v66, 0xbfb8aa3b, v60
	v_mul_f32_e32 v67, 0xbfb8aa3b, v61
	v_exp_f32_e32 v66, v66
	v_exp_f32_e32 v67, v67
	v_mul_f32_e32 v68, 0xbfb8aa3b, v62
	v_mul_f32_e32 v69, 0xbfb8aa3b, v63
	v_exp_f32_e32 v68, v68
	v_exp_f32_e32 v69, v69
	v_add_f32_e32 v66, 1.0, v66
	v_add_f32_e32 v67, 1.0, v67
	v_rcp_f32_e32 v66, v66
	v_rcp_f32_e32 v67, v67
	v_add_f32_e32 v68, 1.0, v68
	v_add_f32_e32 v69, 1.0, v69
	v_rcp_f32_e32 v68, v68
	v_rcp_f32_e32 v69, v69
	v_pk_mul_f32 v[56:57], v[56:57], v[64:65] op_sel_hi:[1,0]
	v_pk_mul_f32 v[60:61], v[60:61], v[66:67]
	v_pk_mul_f32 v[58:59], v[58:59], v[64:65] op_sel_hi:[1,0]
	v_pk_mul_f32 v[56:57], v[56:57], v[60:61]
	v_pk_mul_f32 v[60:61], v[62:63], v[68:69]
	v_pk_mul_f32 v[52:53], v[52:53], v[64:65] op_sel_hi:[1,0]
	v_pk_mul_f32 v[58:59], v[58:59], v[60:61]
	v_cvt_pk_bf16_f32 v56, v56, v57
	v_cvt_pk_bf16_f32 v57, v58, v59
	v_mul_f32_e32 v58, 0xbfb8aa3b, v52
	v_mul_f32_e32 v59, 0xbfb8aa3b, v53
	v_pk_mul_f32 v[54:55], v[54:55], v[64:65] op_sel_hi:[1,0]
	v_exp_f32_e32 v58, v58
	v_exp_f32_e32 v59, v59
	v_mul_f32_e32 v60, 0xbfb8aa3b, v54
	v_mul_f32_e32 v61, 0xbfb8aa3b, v55
	v_exp_f32_e32 v60, v60
	v_exp_f32_e32 v61, v61
	v_add_f32_e32 v58, 1.0, v58
	v_add_f32_e32 v59, 1.0, v59
	v_rcp_f32_e32 v58, v58
	v_rcp_f32_e32 v59, v59
	v_add_f32_e32 v60, 1.0, v60
	v_add_f32_e32 v61, 1.0, v61
	v_rcp_f32_e32 v60, v60
	v_rcp_f32_e32 v61, v61
	v_pk_mul_f32 v[48:49], v[48:49], v[64:65] op_sel_hi:[1,0]
	v_pk_mul_f32 v[52:53], v[52:53], v[58:59]
	v_pk_mul_f32 v[50:51], v[50:51], v[64:65] op_sel_hi:[1,0]
	v_pk_mul_f32 v[48:49], v[48:49], v[52:53]
	s_and_b64 vcc, exec, s[6:7]
	v_cvt_pk_bf16_f32 v58, v48, v49
	v_pk_mul_f32 v[48:49], v[54:55], v[60:61]
	s_nop 0
	v_pk_mul_f32 v[48:49], v[50:51], v[48:49]
	s_nop 0
	v_cvt_pk_bf16_f32 v59, v48, v49
	v_mov_b64_e32 v[48:49], s[56:57]
	v_mad_i64_i32 v[48:49], s[38:39], v65, s81, v[48:49]
	v_lshl_add_u64 v[48:49], v[144:145], 1, v[48:49]
	global_store_dwordx4 v[48:49], v[56:59], off
	s_cbranch_vccnz .LBB0_158
	v_fmamk_f32 v48, v177, 0x3a800000, v166
	v_mul_f32_e32 v49, 0x4b800000, v48
	v_cmp_gt_f32_e32 vcc, s80, v48
	s_nop 1
	v_cndmask_b32_e32 v48, v48, v49, vcc
	v_rsq_f32_e32 v48, v48
	s_nop 0
	v_mul_f32_e32 v49, 0x45800000, v48
	v_cndmask_b32_e32 v72, v48, v49, vcc
; __device__ __forceinline__ unsigned cvt_pk_bf16(float lo, float hi) { cvf32x2_t v = {lo, hi}; cvbf16x2_t b = __builtin_convertvector(v, cvbf16x2_t); return __builtin_bit_cast(unsigned, b); }
; __device__ __forceinline__ float fsilu(float x) { return x * fsigm(x); }
; __device__ __forceinline__ float row_rs(const float* ssq, int row) { return ssq ? rsqrtf(ssq[row] * (1.f / 1024.f) + RMS_EPS) : 1.f; }
;     __device__ __forceinline__ void operator()(const f32x4 (&acc)[2][2][4][2], const Unit& u, int wr, int wc, int fr, int fq) const {
;     ...
;             for (int m = 0; m < 4; ++m) { const int row = row0 + ai * HALF + m * 16; const float rs = row_rs(ssq, row);
;                 u32x4 w; unsigned pk[4];
; #pragma unroll
;                 for (int n = 0; n < 2; ++n) { const f32x4 g = acc[ai][0][m][n] * rs, up = acc[ai][1][m][n] * rs;
;                     pk[2 * n] = cvt_pk_bf16(fsilu(g[0]) * up[0], fsilu(g[1]) * up[1]); pk[2 * n + 1] = cvt_pk_bf16(fsilu(g[2]) * up[2], fsilu(g[3]) * up[3]); }
;                 w.x = pk[0]; w.y = pk[1]; w.z = pk[2]; w.w = pk[3];
;                 st_wt16(H + (size_t)row * ldh + col0, w); }
.LBB0_158:
	v_pk_mul_f32 v[44:45], v[44:45], v[72:73] op_sel_hi:[1,0]
	v_pk_mul_f32 v[48:49], v[42:43], v[72:73] op_sel_hi:[1,0]
	v_pk_mul_f32 v[42:43], v[40:41], v[72:73] op_sel_hi:[1,0]
	v_mul_f32_e32 v40, 0xbfb8aa3b, v44
	v_exp_f32_e32 v41, v40
	v_mul_f32_e32 v40, 0xbfb8aa3b, v45
	v_exp_f32_e32 v51, v40
	v_pk_mul_f32 v[46:47], v[46:47], v[72:73] op_sel_hi:[1,0]
	v_add_f32_e32 v41, 1.0, v41
	v_rcp_f32_e32 v50, v41
	v_add_f32_e32 v41, 1.0, v51
	v_mul_f32_e32 v51, 0xbfb8aa3b, v46
	v_exp_f32_e32 v52, v51
	v_mul_f32_e32 v51, 0xbfb8aa3b, v47
	v_exp_f32_e32 v53, v51
	v_rcp_f32_e32 v51, v41
	v_add_f32_e32 v41, 1.0, v52
	v_rcp_f32_e32 v52, v41
	v_add_f32_e32 v41, 1.0, v53
	v_rcp_f32_e32 v53, v41
	v_pk_mul_f32 v[44:45], v[44:45], v[50:51]
	v_pk_mul_f32 v[36:37], v[36:37], v[72:73] op_sel_hi:[1,0]
	v_pk_mul_f32 v[42:43], v[42:43], v[44:45]
	v_pk_mul_f32 v[44:45], v[46:47], v[52:53]
	v_mul_f32_e32 v41, 0xbfb8aa3b, v36
	v_pk_mul_f32 v[44:45], v[48:49], v[44:45]
	v_cvt_pk_bf16_f32 v42, v42, v43
	v_cvt_pk_bf16_f32 v43, v44, v45
	v_exp_f32_e32 v41, v41
	v_mul_f32_e32 v44, 0xbfb8aa3b, v37
	v_exp_f32_e32 v45, v44
	v_pk_mul_f32 v[38:39], v[38:39], v[72:73] op_sel_hi:[1,0]
	v_add_f32_e32 v41, 1.0, v41
	v_rcp_f32_e32 v44, v41
	v_add_f32_e32 v41, 1.0, v45
	v_mul_f32_e32 v45, 0xbfb8aa3b, v38
	v_exp_f32_e32 v46, v45
	v_mul_f32_e32 v45, 0xbfb8aa3b, v39
	v_exp_f32_e32 v47, v45
	v_rcp_f32_e32 v45, v41
	v_add_f32_e32 v41, 1.0, v46
	v_rcp_f32_e32 v46, v41
	v_add_f32_e32 v41, 1.0, v47
	v_rcp_f32_e32 v47, v41
	v_pk_mul_f32 v[32:33], v[32:33], v[72:73] op_sel_hi:[1,0]
	v_pk_mul_f32 v[36:37], v[36:37], v[44:45]
	v_pk_mul_f32 v[34:35], v[34:35], v[72:73] op_sel_hi:[1,0]
	v_pk_mul_f32 v[32:33], v[32:33], v[36:37]
	v_add_u32_e32 v54, 0x90, v146
	v_cvt_pk_bf16_f32 v44, v32, v33
	v_pk_mul_f32 v[32:33], v[38:39], v[46:47]
	v_mov_b32_e32 v40, 1.0
	v_pk_mul_f32 v[32:33], v[34:35], v[32:33]
	s_and_b64 vcc, exec, s[6:7]
	v_cvt_pk_bf16_f32 v45, v32, v33
	v_mov_b64_e32 v[32:33], s[56:57]
	v_mad_i64_i32 v[32:33], s[38:39], v54, s81, v[32:33]
	v_lshl_add_u64 v[32:33], v[144:145], 1, v[32:33]
	global_store_dwordx4 v[32:33], v[42:45], off
	v_mov_b32_e32 v32, 1.0
	s_cbranch_vccnz .LBB0_160
	v_fmamk_f32 v32, v178, 0x3a800000, v166
	v_mul_f32_e32 v33, 0x4b800000, v32
	v_cmp_gt_f32_e32 vcc, s80, v32
	s_nop 1
	v_cndmask_b32_e32 v32, v32, v33, vcc
	v_rsq_f32_e32 v32, v32
	s_nop 0
	v_mul_f32_e32 v33, 0x45800000, v32
	v_cndmask_b32_e32 v32, v32, v33, vcc
.LBB0_160:
	v_add_u32_e32 v33, 0xa0, v146
	v_pk_mul_f32 v[28:29], v[28:29], v[32:33] op_sel_hi:[1,0]
	v_pk_mul_f32 v[30:31], v[30:31], v[32:33] op_sel_hi:[1,0]
	v_mul_f32_e32 v34, 0xbfb8aa3b, v28
	v_mul_f32_e32 v35, 0xbfb8aa3b, v29
	v_exp_f32_e32 v34, v34
	v_exp_f32_e32 v35, v35
	v_mul_f32_e32 v36, 0xbfb8aa3b, v30
	v_mul_f32_e32 v37, 0xbfb8aa3b, v31
	v_exp_f32_e32 v36, v36
	v_exp_f32_e32 v37, v37
	v_add_f32_e32 v34, 1.0, v34
	v_add_f32_e32 v35, 1.0, v35
	v_rcp_f32_e32 v34, v34
	v_rcp_f32_e32 v35, v35
	v_add_f32_e32 v36, 1.0, v36
	v_add_f32_e32 v37, 1.0, v37
	v_rcp_f32_e32 v36, v36
	v_rcp_f32_e32 v37, v37
	v_pk_mul_f32 v[24:25], v[24:25], v[32:33] op_sel_hi:[1,0]
	v_pk_mul_f32 v[28:29], v[28:29], v[34:35]
	v_pk_mul_f32 v[26:27], v[26:27], v[32:33] op_sel_hi:[1,0]
	v_pk_mul_f32 v[24:25], v[24:25], v[28:29]
	v_pk_mul_f32 v[28:29], v[30:31], v[36:37]
	v_pk_mul_f32 v[20:21], v[20:21], v[32:33] op_sel_hi:[1,0]
	v_pk_mul_f32 v[26:27], v[26:27], v[28:29]
	v_cvt_pk_bf16_f32 v24, v24, v25
	v_cvt_pk_bf16_f32 v25, v26, v27
	v_mul_f32_e32 v26, 0xbfb8aa3b, v20
	v_mul_f32_e32 v27, 0xbfb8aa3b, v21
	v_pk_mul_f32 v[22:23], v[22:23], v[32:33] op_sel_hi:[1,0]
	v_exp_f32_e32 v26, v26
	v_exp_f32_e32 v27, v27
	v_mul_f32_e32 v28, 0xbfb8aa3b, v22
	v_mul_f32_e32 v29, 0xbfb8aa3b, v23
	v_exp_f32_e32 v28, v28
	v_exp_f32_e32 v29, v29
	v_add_f32_e32 v26, 1.0, v26
	v_add_f32_e32 v27, 1.0, v27
	v_rcp_f32_e32 v26, v26
	v_rcp_f32_e32 v27, v27
	v_add_f32_e32 v28, 1.0, v28
	v_add_f32_e32 v29, 1.0, v29
	v_rcp_f32_e32 v28, v28
	v_rcp_f32_e32 v29, v29
	v_pk_mul_f32 v[16:17], v[16:17], v[32:33] op_sel_hi:[1,0]
	v_pk_mul_f32 v[20:21], v[20:21], v[26:27]
	v_pk_mul_f32 v[18:19], v[18:19], v[32:33] op_sel_hi:[1,0]
	v_pk_mul_f32 v[16:17], v[16:17], v[20:21]
	s_and_b64 vcc, exec, s[6:7]
	v_cvt_pk_bf16_f32 v26, v16, v17
	v_pk_mul_f32 v[16:17], v[22:23], v[28:29]
	s_nop 0
	v_pk_mul_f32 v[16:17], v[18:19], v[16:17]
	s_nop 0
	v_cvt_pk_bf16_f32 v27, v16, v17
	v_mov_b64_e32 v[16:17], s[56:57]
	v_mad_i64_i32 v[16:17], s[38:39], v33, s81, v[16:17]
	v_lshl_add_u64 v[16:17], v[144:145], 1, v[16:17]
	global_store_dwordx4 v[16:17], v[24:27], off
	s_cbranch_vccnz .LBB0_162
	v_fmamk_f32 v16, v179, 0x3a800000, v166
	v_mul_f32_e32 v17, 0x4b800000, v16
	v_cmp_gt_f32_e32 vcc, s80, v16
	s_nop 1
	v_cndmask_b32_e32 v16, v16, v17, vcc
	v_rsq_f32_e32 v16, v16
	s_nop 0
	v_mul_f32_e32 v17, 0x45800000, v16
	v_cndmask_b32_e32 v40, v16, v17, vcc
